# v19
# baseline (speedup 1.0000x reference)
.LBB0_1372:
	s_add_i32 s40, s84, -2
	s_max_i32 s40, s40, 0
	s_lshl_b32 s12, s40, 13
	s_mov_b32 s13, 0
	s_lshl_b32 s24, s83, 13
	s_add_i32 m0, s74, s24
	v_lshl_add_u64 v[80:81], v[134:135], 0, s[12:13]
	global_load_lds_dwordx4 v[80:81], off
	s_lshl_b32 s12, s40, 14
	s_lshl_b32 s24, s83, 14
	s_add_i32 s24, s74, s24
	s_add_i32 m0, s24, 0x6000
	v_lshl_add_u64 v[80:81], v[132:133], 0, s[12:13]
	global_load_lds_dwordx4 v[80:81], off
	s_add_i32 m0, s24, 0x8000
	v_lshl_add_u64 v[80:81], v[80:81], 0, s[26:27]
	global_load_lds_dwordx4 v[80:81], off
	v_lshl_add_u32 v126, s81, 13, v153
	s_lshl_b32 s12, s81, 8
	v_add_u32_e32 v115, v126, v152
	v_add_u32_e32 v114, s12, v154
	ds_read_b128 v[208:211], v115 offset:4096
	ds_read_b128 v[80:83], v114 offset:128
	ds_read_b128 v[84:87], v114 offset:144
	ds_read_b128 v[88:91], v114 offset:192
	ds_read_b128 v[92:95], v114 offset:208
	ds_read_b128 v[224:227], v115
	ds_read_b128 v[192:195], v114
	ds_read_b128 v[196:199], v114 offset:16
	ds_read_b128 v[200:203], v114 offset:64
	ds_read_b128 v[204:207], v114 offset:80
	v_med3_i32 v118, v113, 0, v137
	v_lshlrev_b32_e32 v119, 2, v118
	global_load_dword v164, v119, s[54:55]
	v_add_u32_e32 v116, v126, v155
	v_add_u32_e32 v117, v126, v156
	v_add_u32_e32 v118, v126, v157
	s_waitcnt lgkmcnt(5)
	v_mfma_f32_32x32x16_bf16 v[80:95], v[208:211], v[108:111], v[80:95]
	ds_read_b128 v[212:215], v116 offset:4096
	ds_read_b128 v[228:231], v116
	s_waitcnt lgkmcnt(2)
	v_mfma_f32_32x32x16_bf16 v[192:207], v[224:227], v[108:111], v[192:207]
	ds_read_b128 v[216:219], v117 offset:4096
	ds_read_b128 v[232:235], v117
	s_waitcnt lgkmcnt(2)
	v_mfma_f32_32x32x16_bf16 v[80:95], v[212:215], v[104:107], v[80:95]
	v_mfma_f32_32x32x16_bf16 v[192:207], v[228:231], v[104:107], v[192:207]
	ds_read_b128 v[220:223], v118 offset:4096
	ds_read_b128 v[236:239], v118
	s_waitcnt lgkmcnt(2)
	v_mfma_f32_32x32x16_bf16 v[80:95], v[216:219], v[100:103], v[80:95]
	v_mfma_f32_32x32x16_bf16 v[192:207], v[232:235], v[100:103], v[192:207]
	s_waitcnt lgkmcnt(0)
	v_mfma_f32_32x32x16_bf16 v[80:95], v[220:223], v[96:99], v[80:95]
	v_mfma_f32_32x32x16_bf16 v[192:207], v[236:239], v[96:99], v[192:207]
	s_and_b64 vcc, exec, s[8:9]
	s_cbranch_vccnz .LBB0_1375
	v_sub_u32_e32 v242, v148, v131
	v_cvt_f32_i32_e32 v242, v242
	v_lshl_add_u32 v243, s80, 8, v160
	v_mul_f32_e32 v242, v139, v242
	ds_write_b32 v243, v242
.LBB0_1375:
	s_mov_b32 s12, s80
	s_nop 7
	v_max_f32_e32 v119, v81, v81
	v_max_f32_e32 v120, v80, v80
	v_max_f32_e32 v119, v120, v119
	v_max3_f32 v119, v119, v82, v83
	v_max_f32_e32 v240, v193, v193
	v_max_f32_e32 v241, v192, v192
	v_max3_f32 v119, v119, v84, v85
	v_max_f32_e32 v240, v241, v240
	v_max3_f32 v119, v119, v86, v87
	v_max3_f32 v240, v240, v194, v195
	v_max3_f32 v119, v119, v88, v89
	v_max3_f32 v240, v240, v196, v197
	v_max3_f32 v119, v119, v90, v91
	v_max3_f32 v240, v240, v198, v199
	v_max3_f32 v119, v119, v92, v93
	v_max3_f32 v240, v240, v200, v201
	v_max3_f32 v119, v119, v94, v95
	v_max3_f32 v240, v240, v202, v203
	v_max3_f32 v240, v240, v204, v205
	v_max3_f32 v240, v240, v206, v207
	v_cmp_lt_f32_e32 vcc, v119, v112
	s_cmp_eq_u64 vcc, exec
	s_cbranch_scc0 .LBB0_1377
	s_add_i32 s84, s84, -1
	s_cmp_lt_i32 s84, 1
	s_waitcnt vmcnt(4) lgkmcnt(0)
	s_barrier
	v_subrev_u32_e32 v113, 64, v113
	s_waitcnt vmcnt(0)
	v_mov_b32_e32 v148, v164
	s_mov_b32 s80, s83
	s_mov_b32 s83, s81
	s_mov_b32 s81, s12
	s_cbranch_scc0 .LBB0_1378
	v_mov_b32_e32 v241, v240
	s_nop 1
	v_permlane32_swap_b32_e32 v240, v241
	v_max_f32_e32 v241, v241, v241
	v_max_f32_e32 v240, v240, v240
	v_max_f32_e32 v166, v240, v241
	v_mov_b64_e32 v[64:65], v[192:193]
	v_mov_b64_e32 v[66:67], v[194:195]
	v_mov_b64_e32 v[68:69], v[196:197]
	v_mov_b64_e32 v[70:71], v[198:199]
	v_mov_b64_e32 v[72:73], v[200:201]
	v_mov_b64_e32 v[74:75], v[202:203]
	v_mov_b64_e32 v[76:77], v[204:205]
	v_mov_b64_e32 v[78:79], v[206:207]
	s_mov_b64 s[42:43], 0
	s_mov_b64 s[40:41], s[10:11]
	s_branch .LBB0_1330

.LBB0_1378:
	v_cmp_lt_f32_e32 vcc, v240, v112
	s_cmp_eq_u64 vcc, exec
	s_cbranch_scc1 .LBB0_1372
